# ffn-in GEMM tile transition: no vmcnt(0) drain at tile start, row-scale loads hoisted before the epilogue stores, first two stage waits count the epilogue stores
# speedup vs baseline: 1.0405x; 1.0017x over previous
; #define PG8_STAGE(bufoff, gbase, voff) do { _Pragma("unroll") for (int _i = 0; _i < 2; ++_i) \
;         __builtin_amdgcn_global_load_lds((const unsigned*)((const char*)(gbase) + (voff)[_i]), (LAS unsigned*)(lds + (bufoff) + ldsw + _i * 8192), 16, 0, 0); } while (0)
; #define PG8_WAIT_V(n) asm volatile("s_waitcnt vmcnt(" #n ")" ::: "memory")
; #define PG8_BAR __builtin_amdgcn_s_barrier()
; template <class Epi, class Sched>
; __device__ __forceinline__ void gemm_phase(LAS unsigned char* lds, const Gemm g, const Sched& S, const Epi& E, const int tid) {
;     ...
;     for (int i = 0; i < 2; ++i) { int R, C; stage_rc(tid * 16 + i * 8192, R, C); const int Rb = Epi::PERM ? ((R & ~31) + perm32(R & 31)) : R;
;         voffA[i] = (unsigned)(R * P + C) * 2u; voffB[i] = (unsigned)(Rb * P + C) * 2u; }
;     const size_t kstep = (size_t)(BK * 2);
;     const size_t hstep = (size_t)HALF * P * 2;
;     const size_t tstep = 2 * hstep;
;     const unsigned ldsw = (unsigned)wid * 1024u;
;     const int aoff = lds_byte(wr * 64 + fr, fq * 8), boff = lds_byte(wc * 32 + fr, fq * 8);
;     ...
;     Unit cur, nxt; int ui = 0;
;     if (!S.next(0, cur)) return;
;     f32x4 acc[2][2][4][2];
; #pragma unroll
;     for (int a = 0; a < 2; ++a)
; #pragma unroll
;         for (int b = 0; b < 2; ++b)
; #pragma unroll
;             for (int m = 0; m < 4; ++m)
; #pragma unroll
;                 for (int n = 0; n < 2; ++n) acc[a][b][m][n] = (f32x4){0.f, 0.f, 0.f, 0.f};
;     bf16x8 At[4][2], B0[2][2], B1[2][2];
;     const char* cA = (const char*)g.A + (size_t)cur.pm * tstep + (size_t)cur.koff * 2; const char* cB = (const char*)g.Bt + (size_t)cur.pn * tstep + (size_t)cur.koff * 2;
;     E.prep(cur, lds + STAGE_BYTES, tid);
;     PG8_STAGE(PG8_SB(0, 0), cB, voffB); PG8_STAGE(PG8_SB(0, 1), cB + hstep, voffB); PG8_STAGE(PG8_SA(0, 0), cA, voffA); PG8_STAGE(PG8_SA(0, 1), cA + hstep, voffA);
;     if (wr == 1) PG8_BAR;
;     PG8_WAIT_V(2); PG8_BAR;
.LBB0_22:
	s_mov_b32 s95, 0x7fffffff
	s_or_b64 exec, exec, s[12:13]
	v_mov_b32_e32 v0, s15
	v_lshlrev_b32_e32 v2, 4, v144
	v_readfirstlane_b32 s28, v0
	v_ashrrev_i32_e32 v0, 31, v144
	v_lshrrev_b32_e32 v0, 26, v0
	v_add_u32_e32 v0, v144, v0
	v_ashrrev_i32_e32 v10, 6, v0
	v_bfe_i32 v0, v144, 27, 1
	v_lshrrev_b32_e32 v0, 22, v0
	v_add_u32_e32 v0, v2, v0
	v_and_b32_e32 v0, 0xfffffc00, v0
	v_sub_u32_e32 v0, v2, v0
	s_add_u32 s21, s6, 0x2600000
	v_lshrrev_b32_e32 v3, 4, v0
	s_addc_u32 s36, s7, 0
	v_bitop3_b32 v0, v3, v0, 32 bitop3:0x6c
	s_add_u32 s42, s6, 0x1480000
	v_ashrrev_i32_e32 v4, 31, v0
	s_addc_u32 s43, s7, 0
	s_ashr_i32 s53, s52, 31
	v_lshrrev_b32_e32 v4, 26, v4
	s_lshl_b64 s[12:13], s[52:53], 19
	v_add_u32_e32 v4, v0, v4
	s_add_u32 s54, s21, s12
	v_lshlrev_b32_e32 v3, 3, v10
	v_ashrrev_i32_e32 v11, 6, v4
	v_and_b32_e32 v4, 0xc0, v4
	s_addc_u32 s55, s36, s13
	s_bfe_i64 s[12:13], s[28:29], 0x80000
	v_and_b32_e32 v3, -16, v3
	v_sub_u32_e32 v0, v0, v4
	s_lshl_b64 s[12:13], s[12:13], 19
	v_add_u32_e32 v3, v11, v3
	v_ashrrev_i16_sdwa v0, v186, sext(v0) dst_sel:DWORD dst_unused:UNUSED_PAD src0_sel:DWORD src1_sel:BYTE_0
	s_add_u32 s56, s42, s12
	v_lshlrev_b32_e32 v5, 5, v10
	v_bfe_i32 v12, v0, 0, 16
	v_lshlrev_b32_e32 v0, 1, v3
	v_lshrrev_b32_e32 v4, 2, v3
	v_and_b32_e32 v6, 3, v11
	s_mov_b32 s12, 0x1fffe0
	v_and_b32_e32 v5, 32, v5
	v_and_b32_e32 v0, 24, v0
	v_and_b32_e32 v4, 4, v4
	v_and_or_b32 v6, v3, s12, v6
	v_or3_b32 v0, v6, v4, v0
	v_add_lshl_u32 v4, v5, v12, 1
	v_add_u32_e32 v2, 0x2000, v2
	v_lshl_add_u32 v132, v3, 11, v4
	v_ashrrev_i32_e32 v3, 31, v2
	v_lshrrev_b32_e32 v3, 22, v3
	v_add_u32_e32 v3, v2, v3
	v_ashrrev_i32_e32 v13, 10, v3
	v_mul_i32_i24_e32 v3, 0x400, v13
	v_sub_u32_e32 v2, v2, v3
	v_lshrrev_b32_e32 v3, 4, v2
	v_bitop3_b32 v2, v3, v2, 32 bitop3:0x6c
	v_lshl_add_u32 v0, v0, 11, v4
	v_ashrrev_i32_e32 v4, 31, v2
	v_lshrrev_b32_e32 v4, 26, v4
	v_add_u32_e32 v4, v2, v4
	v_lshlrev_b32_e32 v3, 3, v13
	v_ashrrev_i32_e32 v14, 6, v4
	v_and_b32_e32 v4, 0xc0, v4
	s_addc_u32 s57, s43, s13
	v_and_b32_e32 v3, -16, v3
	v_sub_u32_e32 v2, v2, v4
	s_ashr_i32 s22, s14, 6
	v_add_u32_e32 v3, v14, v3
	v_ashrrev_i16_sdwa v2, v186, sext(v2) dst_sel:DWORD dst_unused:UNUSED_PAD src0_sel:DWORD src1_sel:BYTE_0
	s_lshl_b32 s28, s22, 10
	v_lshlrev_b32_e32 v5, 5, v13
	v_bfe_i32 v15, v2, 0, 16
	v_lshlrev_b32_e32 v2, 1, v3
	v_lshrrev_b32_e32 v4, 2, v3
	v_and_b32_e32 v6, 3, v14
	s_add_i32 s44, s28, 0
	v_and_b32_e32 v5, 32, v5
	v_and_b32_e32 v2, 24, v2
	v_and_b32_e32 v4, 4, v4
	v_and_or_b32 v6, v3, s12, v6
	s_add_i32 m0, s44, 0x10000
	s_ashr_i32 s19, s14, 8
	v_or3_b32 v2, v6, v4, v2
	v_add_lshl_u32 v4, v5, v15, 1
	global_load_lds_dwordx4 v0, s[56:57]
	s_add_i32 m0, s44, 0x12000
	v_lshl_add_u32 v136, v2, 11, v4
	s_add_u32 s12, s56, 0x40000
	global_load_lds_dwordx4 v136, s[56:57]
	s_addc_u32 s13, s57, 0
	s_add_i32 m0, s44, 0x14000
	s_add_i32 s45, s44, 0x2000
	global_load_lds_dwordx4 v0, s[12:13]
	s_add_i32 m0, s44, 0x16000
	v_lshl_add_u32 v134, v3, 11, v4
	global_load_lds_dwordx4 v136, s[12:13]
	s_mov_b32 m0, s44
	s_add_u32 s12, s54, 0x40000
	global_load_lds_dwordx4 v132, s[54:55]
	s_mov_b32 m0, s45
	s_addc_u32 s13, s55, 0
	s_add_i32 s53, s44, 0x4000
	global_load_lds_dwordx4 v134, s[54:55]
	s_mov_b32 m0, s53
	s_add_i32 s60, s44, 0x6000
	global_load_lds_dwordx4 v132, s[12:13]
	s_mov_b32 m0, s60
	v_mov_b32_e32 v137, v1
	global_load_lds_dwordx4 v134, s[12:13]
	v_mov_b32_e32 v133, v1
	v_mov_b32_e32 v135, v1
	s_cmp_eq_u32 s19, 1
	v_lshl_add_u64 v[8:9], s[56:57], 0, v[0:1]
	v_lshl_add_u64 v[6:7], s[56:57], 0, v[136:137]
	v_lshl_add_u64 v[2:3], s[54:55], 0, v[132:133]
	s_cselect_b64 s[12:13], -1, 0
	s_cmp_lg_u32 s19, 1
	v_lshl_add_u64 v[4:5], s[54:55], 0, v[134:135]
	s_cbranch_scc1 .LBB0_24
	s_barrier

; #define PG8_STAGE(bufoff, gbase, voff) do { _Pragma("unroll") for (int _i = 0; _i < 2; ++_i) \
;         __builtin_amdgcn_global_load_lds((const unsigned*)((const char*)(gbase) + (voff)[_i]), (LAS unsigned*)(lds + (bufoff) + ldsw + _i * 8192), 16, 0, 0); } while (0)
; #define PG8_LDA(dst, b, h) do { _Pragma("unroll") for (int m = 0; m < 4; ++m) _Pragma("unroll") for (int k = 0; k < 2; ++k) dst[m][k] = *(const LAS bf16x8*)(lds + PG8_SA(b, h) + aoff + m * 2048 + k * 1024); } while (0)
; #define PG8_LDB(dst, b, h) do { _Pragma("unroll") for (int n = 0; n < 2; ++n) _Pragma("unroll") for (int k = 0; k < 2; ++k) dst[n][k] = *(const LAS bf16x8*)(lds + PG8_SB(b, h) + boff + n * 2048 + k * 1024); } while (0)
; #define PG8_WAIT_V(n) asm volatile("s_waitcnt vmcnt(" #n ")" ::: "memory")
; template <class Epi, class Sched>
; __device__ __forceinline__ void gemm_phase(LAS unsigned char* lds, const Gemm g, const Sched& S, const Epi& E, const int tid) {
;     ...
;     for (;;) {
;         const bool has_next = S.next(ui + 1, nxt);
;         const char* nA = has_next ? (const char*)g.A + (size_t)nxt.pm * tstep + (size_t)nxt.koff * 2 : cA; const char* nB = has_next ? (const char*)g.Bt + (size_t)nxt.pn * tstep + (size_t)nxt.koff * 2 : cB;
;         const int nt = cur.nt;
;         for (int t = 0; t < nt; t += 2) {
;             if constexpr (Epi::CHAIN) { if (t == 8 || t == 12) { E.mid(acc, cur, t == 8 ? 0 : 1, wr, wc, fr, fq); PG8_SCHED; } }
;             const bool last = (t == nt - 2);
;             const char* a1 = cA + (size_t)(t + 1) * kstep;
;             const char* a2 = last ? nA : cA + (size_t)(t + 2) * kstep; const char* b2 = last ? nB : cB + (size_t)(t + 2) * kstep;
;             const char* a3 = a2 + kstep; const char* b3 = b2 + kstep;
;             PG8_LDB(B0, 0, 0); PG8_LDB(B1, 0, 1); PG8_SCHED; PG8_LDA(At, 0, 0); PG8_STAGE(PG8_SA(1, 1), a1 + hstep, voffA);
;             PG8_WAIT_V(8); PG8_WAIT_L(0); PG8_BAR; PG8_MMA(0, 0, At, B0); PG8_MMA(0, 1, At, B1); PG8_BAR; PG8_SCHED;
;     ...
;         if (!(Epi::CHAIN && nxt.seg != 0))
; #pragma unroll
;         for (int a = 0; a < 2; ++a)
; #pragma unroll
;             for (int b = 0; b < 2; ++b)
; #pragma unroll
;                 for (int m = 0; m < 4; ++m)
; #pragma unroll
;                     for (int n = 0; n < 2; ++n) acc[a][b][m][n] = (f32x4){0.f, 0.f, 0.f, 0.f};
;         cur = nxt; cA = nA; cB = nB; ++ui;
.LBB0_29:
	s_ashr_i32 s23, s22, 31
	s_lshl_b64 s[26:27], s[22:23], 19
	s_add_u32 s48, s21, s26
	s_addc_u32 s49, s36, s27
	s_and_b64 s[26:27], s[6:7], exec
	s_cselect_b32 s23, s49, s55
	s_cselect_b32 s70, s48, s54
	s_ashr_i32 s19, s18, 31
	s_lshl_b64 s[26:27], s[18:19], 19
	s_add_u32 s50, s42, s26
	s_addc_u32 s51, s43, s27
	s_and_b64 s[26:27], s[6:7], exec
	s_cselect_b32 s19, s51, s57
	s_cselect_b32 s71, s50, s56
	s_add_u32 s54, s54, 0x40080
	s_addc_u32 s55, s55, 0
	s_add_u32 s76, s56, 0x100
	v_mov_b32_e32 v2, 0
	s_addc_u32 s79, s57, 0
	s_mov_b32 s72, -2
	v_mov_b32_e32 v3, v2
	v_mov_b32_e32 v4, v2
	v_mov_b32_e32 v5, v2
	v_mov_b32_e32 v6, v2
	v_mov_b32_e32 v7, v2
	v_mov_b32_e32 v8, v2
	v_mov_b32_e32 v9, v2
	v_mov_b32_e32 v14, v2
	v_mov_b32_e32 v15, v2
	v_mov_b32_e32 v16, v2
	v_mov_b32_e32 v17, v2
	v_mov_b32_e32 v22, v2
	v_mov_b32_e32 v23, v2
	v_mov_b32_e32 v24, v2
	v_mov_b32_e32 v25, v2
	v_mov_b32_e32 v30, v2
	v_mov_b32_e32 v31, v2
	v_mov_b32_e32 v32, v2
	v_mov_b32_e32 v33, v2
	v_mov_b32_e32 v38, v2
	v_mov_b32_e32 v39, v2
	v_mov_b32_e32 v40, v2
	v_mov_b32_e32 v41, v2
	v_mov_b32_e32 v46, v2
	v_mov_b32_e32 v47, v2
	v_mov_b32_e32 v48, v2
	v_mov_b32_e32 v49, v2
	v_mov_b32_e32 v54, v2
	v_mov_b32_e32 v55, v2
	v_mov_b32_e32 v56, v2
	v_mov_b32_e32 v57, v2
	v_mov_b32_e32 v10, v2
	v_mov_b32_e32 v11, v2
	v_mov_b32_e32 v12, v2
	v_mov_b32_e32 v13, v2
	v_mov_b32_e32 v18, v2
	v_mov_b32_e32 v19, v2
	v_mov_b32_e32 v20, v2
	v_mov_b32_e32 v21, v2
	v_mov_b32_e32 v26, v2
	v_mov_b32_e32 v27, v2
	v_mov_b32_e32 v28, v2
	v_mov_b32_e32 v29, v2
	v_mov_b32_e32 v34, v2
	v_mov_b32_e32 v35, v2
	v_mov_b32_e32 v36, v2
	v_mov_b32_e32 v37, v2
	v_mov_b32_e32 v42, v2
	v_mov_b32_e32 v43, v2
	v_mov_b32_e32 v44, v2
	v_mov_b32_e32 v45, v2
	v_mov_b32_e32 v50, v2
	v_mov_b32_e32 v51, v2
	v_mov_b32_e32 v52, v2
	v_mov_b32_e32 v53, v2
	v_mov_b32_e32 v58, v2
	v_mov_b32_e32 v59, v2
	v_mov_b32_e32 v60, v2
	v_mov_b32_e32 v61, v2
	v_mov_b32_e32 v62, v2
	v_mov_b32_e32 v63, v2
	v_mov_b32_e32 v64, v2
	v_mov_b32_e32 v65, v2
	v_mov_b32_e32 v66, v2
	v_mov_b32_e32 v67, v2
	v_mov_b32_e32 v68, v2
	v_mov_b32_e32 v69, v2
	v_mov_b32_e32 v70, v2
	v_mov_b32_e32 v71, v2
	v_mov_b32_e32 v72, v2
	v_mov_b32_e32 v73, v2
	v_mov_b32_e32 v78, v2
	v_mov_b32_e32 v79, v2
	v_mov_b32_e32 v80, v2
	v_mov_b32_e32 v81, v2
	v_mov_b32_e32 v86, v2
	v_mov_b32_e32 v87, v2
	v_mov_b32_e32 v88, v2
	v_mov_b32_e32 v89, v2
	v_mov_b32_e32 v94, v2
	v_mov_b32_e32 v95, v2
	v_mov_b32_e32 v96, v2
	v_mov_b32_e32 v97, v2
	v_mov_b32_e32 v102, v2
	v_mov_b32_e32 v103, v2
	v_mov_b32_e32 v104, v2
	v_mov_b32_e32 v105, v2
	v_mov_b32_e32 v110, v2
	v_mov_b32_e32 v111, v2
	v_mov_b32_e32 v112, v2
	v_mov_b32_e32 v113, v2
	v_mov_b32_e32 v118, v2
	v_mov_b32_e32 v119, v2
	v_mov_b32_e32 v120, v2
	v_mov_b32_e32 v121, v2
	v_mov_b32_e32 v74, v2
	v_mov_b32_e32 v75, v2
	v_mov_b32_e32 v76, v2
	v_mov_b32_e32 v77, v2
	v_mov_b32_e32 v82, v2
	v_mov_b32_e32 v83, v2
	v_mov_b32_e32 v84, v2
	v_mov_b32_e32 v85, v2
	v_mov_b32_e32 v90, v2
	v_mov_b32_e32 v91, v2
	v_mov_b32_e32 v92, v2
	v_mov_b32_e32 v93, v2
	v_mov_b32_e32 v98, v2
	v_mov_b32_e32 v99, v2
	v_mov_b32_e32 v100, v2
	v_mov_b32_e32 v101, v2
	v_mov_b32_e32 v106, v2
	v_mov_b32_e32 v107, v2
	v_mov_b32_e32 v108, v2
	v_mov_b32_e32 v109, v2
	v_mov_b32_e32 v114, v2
	v_mov_b32_e32 v115, v2
	v_mov_b32_e32 v116, v2
	v_mov_b32_e32 v117, v2
	v_mov_b32_e32 v122, v2
	v_mov_b32_e32 v123, v2
	v_mov_b32_e32 v124, v2
	v_mov_b32_e32 v125, v2
	v_mov_b32_e32 v126, v2
	v_mov_b32_e32 v127, v2
	v_mov_b32_e32 v128, v2
	v_mov_b32_e32 v129, v2
.LBB0_30:
	s_add_u32 s26, s54, 0xfffc0080
	s_addc_u32 s27, s55, -1
	s_add_i32 s30, 0, 0x10000
	s_cmp_eq_u32 s72, 12
	s_cselect_b32 s59, s23, s27
	s_cselect_b32 s58, s70, s26
	v_add_u32_e32 v142, s30, v156
	s_cselect_b32 s57, s19, s79
	s_cselect_b32 s56, s71, s76
	s_add_i32 s81, 0, 0x14000
	ds_read_b128 v[162:165], v142
	ds_read_b128 v[166:169], v142 offset:1024
	ds_read_b128 v[170:173], v142 offset:2048
	ds_read_b128 v[174:177], v142 offset:3072
	v_add_u32_e32 v142, s81, v156
	ds_read_b128 v[178:181], v142
	ds_read_b128 v[198:201], v142 offset:1024
	ds_read_b128 v[202:205], v142 offset:2048
	ds_read_b128 v[206:209], v142 offset:3072
	v_lshl_add_u64 v[142:143], s[54:55], 0, v[138:139]
	s_add_i32 m0, s44, 0xc000
	ds_read_b128 v[210:213], v160
	ds_read_b128 v[214:217], v160 offset:1024
	ds_read_b128 v[218:221], v160 offset:2048
	ds_read_b128 v[222:225], v160 offset:3072
	ds_read_b128 v[226:229], v160 offset:4096
	ds_read_b128 v[230:233], v160 offset:5120
	ds_read_b128 v[234:237], v160 offset:6144
	ds_read_b128 v[238:241], v160 offset:7168
	global_load_lds_dwordx4 v[142:143], off
	v_lshl_add_u64 v[142:143], s[54:55], 0, v[140:141]
	s_add_i32 m0, s44, 0xe000
	s_nop 0
	global_load_lds_dwordx4 v[142:143], off
	s_cmp_eq_u32 s72, s95
	s_cbranch_scc1 .Ltt6_a
	s_waitcnt vmcnt(8)
; #define PG8_STAGE(bufoff, gbase, voff) do { _Pragma("unroll") for (int _i = 0; _i < 2; ++_i) \
;         __builtin_amdgcn_global_load_lds((const unsigned*)((const char*)(gbase) + (voff)[_i]), (LAS unsigned*)(lds + (bufoff) + ldsw + _i * 8192), 16, 0, 0); } while (0)
; #define PG8_LDA(dst, b, h) do { _Pragma("unroll") for (int m = 0; m < 4; ++m) _Pragma("unroll") for (int k = 0; k < 2; ++k) dst[m][k] = *(const LAS bf16x8*)(lds + PG8_SA(b, h) + aoff + m * 2048 + k * 1024); } while (0)
; #define PG8_LDB(dst, b, h) do { _Pragma("unroll") for (int n = 0; n < 2; ++n) _Pragma("unroll") for (int k = 0; k < 2; ++k) dst[n][k] = *(const LAS bf16x8*)(lds + PG8_SB(b, h) + boff + n * 2048 + k * 1024); } while (0)
; #define PG8_MMA(ai, bj, At, Bt) do { __builtin_amdgcn_s_setprio(1); _Pragma("unroll") for (int m = 0; m < 4; ++m) _Pragma("unroll") for (int n = 0; n < 2; ++n) _Pragma("unroll") for (int k = 0; k < 2; ++k) \
;         acc[ai][bj][m][n] = __builtin_amdgcn_mfma_f32_16x16x32_bf16(Bt[n][k], At[m][k], acc[ai][bj][m][n], 0, 0, 0); __builtin_amdgcn_s_setprio(0); } while (0)
; #define PG8_WAIT_V(n) asm volatile("s_waitcnt vmcnt(" #n ")" ::: "memory")
; #define PG8_WAIT_L(n) asm volatile("s_waitcnt lgkmcnt(" #n ")" ::: "memory")
; #define PG8_BAR __builtin_amdgcn_s_barrier()
; #define PG8_SCHED __builtin_amdgcn_sched_barrier(0)
; template <class Epi, class Sched>
; __device__ __forceinline__ void gemm_phase(LAS unsigned char* lds, const Gemm g, const Sched& S, const Epi& E, const int tid) {
;     ...
;             PG8_LDB(B0, 0, 0); PG8_LDB(B1, 0, 1); PG8_SCHED; PG8_LDA(At, 0, 0); PG8_STAGE(PG8_SA(1, 1), a1 + hstep, voffA);
;             PG8_WAIT_V(8); PG8_WAIT_L(0); PG8_BAR; PG8_MMA(0, 0, At, B0); PG8_MMA(0, 1, At, B1); PG8_BAR; PG8_SCHED;
;             PG8_LDA(At, 0, 1); PG8_STAGE(PG8_SB(0, 0), b2, voffB); PG8_STAGE(PG8_SB(0, 1), b2 + hstep, voffB); PG8_STAGE(PG8_SA(0, 0), a2, voffA);
;             PG8_WAIT_V(8); PG8_WAIT_L(0); PG8_BAR; PG8_MMA(1, 0, At, B0); PG8_MMA(1, 1, At, B1); PG8_BAR; PG8_SCHED;
.Ltt6_a:
	s_waitcnt vmcnt(24)
	s_waitcnt lgkmcnt(0)
	s_barrier
	s_setprio 1
	s_waitcnt lgkmcnt(0)
	v_mfma_f32_16x16x32_bf16 v[126:129], v[162:165], v[210:213], v[126:129]
	v_mfma_f32_16x16x32_bf16 v[122:125], v[170:173], v[210:213], v[122:125]
	v_mfma_f32_16x16x32_bf16 v[114:117], v[162:165], v[218:221], v[114:117]
	v_mfma_f32_16x16x32_bf16 v[106:109], v[170:173], v[218:221], v[106:109]
	v_mfma_f32_16x16x32_bf16 v[98:101], v[162:165], v[226:229], v[98:101]
	v_mfma_f32_16x16x32_bf16 v[90:93], v[170:173], v[226:229], v[90:93]
	v_mfma_f32_16x16x32_bf16 v[82:85], v[162:165], v[234:237], v[82:85]
	v_mfma_f32_16x16x32_bf16 v[74:77], v[170:173], v[234:237], v[74:77]
	v_mfma_f32_16x16x32_bf16 v[126:129], v[166:169], v[214:217], v[126:129]
	v_mfma_f32_16x16x32_bf16 v[122:125], v[174:177], v[214:217], v[122:125]
	v_mfma_f32_16x16x32_bf16 v[114:117], v[166:169], v[222:225], v[114:117]
	v_mfma_f32_16x16x32_bf16 v[106:109], v[174:177], v[222:225], v[106:109]
	v_mfma_f32_16x16x32_bf16 v[98:101], v[166:169], v[230:233], v[98:101]
	v_mfma_f32_16x16x32_bf16 v[90:93], v[174:177], v[230:233], v[90:93]
	v_mfma_f32_16x16x32_bf16 v[82:85], v[166:169], v[238:241], v[82:85]
	v_mfma_f32_16x16x32_bf16 v[74:77], v[174:177], v[238:241], v[74:77]
	s_setprio 0
	s_setprio 1
	v_mfma_f32_16x16x32_bf16 v[118:121], v[178:181], v[210:213], v[118:121]
	v_mfma_f32_16x16x32_bf16 v[110:113], v[202:205], v[210:213], v[110:113]
	v_mfma_f32_16x16x32_bf16 v[102:105], v[178:181], v[218:221], v[102:105]
	v_mfma_f32_16x16x32_bf16 v[94:97], v[202:205], v[218:221], v[94:97]
	v_mfma_f32_16x16x32_bf16 v[86:89], v[178:181], v[226:229], v[86:89]
	v_mfma_f32_16x16x32_bf16 v[78:81], v[202:205], v[226:229], v[78:81]
	v_mfma_f32_16x16x32_bf16 v[70:73], v[178:181], v[234:237], v[70:73]
	v_mfma_f32_16x16x32_bf16 v[66:69], v[202:205], v[234:237], v[66:69]
	v_mfma_f32_16x16x32_bf16 v[118:121], v[198:201], v[214:217], v[118:121]
	v_mfma_f32_16x16x32_bf16 v[110:113], v[206:209], v[214:217], v[110:113]
	v_mfma_f32_16x16x32_bf16 v[102:105], v[198:201], v[222:225], v[102:105]
	v_mfma_f32_16x16x32_bf16 v[94:97], v[206:209], v[222:225], v[94:97]
	v_mfma_f32_16x16x32_bf16 v[86:89], v[198:201], v[230:233], v[86:89]
	v_mfma_f32_16x16x32_bf16 v[78:81], v[206:209], v[230:233], v[78:81]
	v_mfma_f32_16x16x32_bf16 v[70:73], v[198:201], v[238:241], v[70:73]
	v_mfma_f32_16x16x32_bf16 v[66:69], v[206:209], v[238:241], v[66:69]
	s_setprio 0
	s_barrier
	s_add_i32 s26, s30, s28
	v_lshl_add_u64 v[142:143], s[56:57], 0, v[0:1]
	s_mov_b32 m0, s26
	ds_read_b128 v[210:213], v160 offset:16384
	ds_read_b128 v[214:217], v160 offset:17408
	ds_read_b128 v[218:221], v160 offset:18432
	ds_read_b128 v[222:225], v160 offset:19456
	ds_read_b128 v[226:229], v160 offset:20480
	ds_read_b128 v[230:233], v160 offset:21504
	ds_read_b128 v[234:237], v160 offset:22528
	ds_read_b128 v[238:241], v160 offset:23552
	global_load_lds_dwordx4 v[142:143], off
	s_add_i32 m0, s26, 0x2000
	s_add_u32 s26, s56, 0x40000
	v_lshl_add_u64 v[182:183], s[56:57], 0, v[136:137]
	s_addc_u32 s27, s57, 0
	s_add_i32 s30, s81, s28
	global_load_lds_dwordx4 v[182:183], off
	v_lshl_add_u64 v[192:193], s[26:27], 0, v[0:1]
	s_mov_b32 m0, s30
	v_lshl_add_u64 v[242:243], s[58:59], 0, v[134:135]
	global_load_lds_dwordx4 v[192:193], off
	v_lshl_add_u64 v[192:193], s[26:27], 0, v[136:137]
	s_add_i32 m0, s30, 0x2000
	s_nop 0
	global_load_lds_dwordx4 v[192:193], off
	v_lshl_add_u64 v[192:193], s[58:59], 0, v[132:133]
	s_mov_b32 m0, s44
	s_nop 0
	global_load_lds_dwordx4 v[192:193], off
	s_mov_b32 m0, s45
	s_nop 0
	global_load_lds_dwordx4 v[242:243], off
	s_cmp_eq_u32 s72, s95
	s_cbranch_scc1 .Ltt6_b
	s_waitcnt vmcnt(8)
.Ltt6_b:
	s_waitcnt vmcnt(24)
	s_waitcnt lgkmcnt(0)
	s_barrier
	s_setprio 1
	s_waitcnt lgkmcnt(0)
	v_mfma_f32_16x16x32_bf16 v[62:65], v[162:165], v[210:213], v[62:65]
	v_mfma_f32_16x16x32_bf16 v[58:61], v[170:173], v[210:213], v[58:61]
	v_mfma_f32_16x16x32_bf16 v[50:53], v[162:165], v[218:221], v[50:53]
	v_mfma_f32_16x16x32_bf16 v[42:45], v[170:173], v[218:221], v[42:45]
	v_mfma_f32_16x16x32_bf16 v[34:37], v[162:165], v[226:229], v[34:37]
	v_mfma_f32_16x16x32_bf16 v[26:29], v[170:173], v[226:229], v[26:29]
	v_mfma_f32_16x16x32_bf16 v[18:21], v[162:165], v[234:237], v[18:21]
	v_mfma_f32_16x16x32_bf16 v[10:13], v[170:173], v[234:237], v[10:13]
	v_mfma_f32_16x16x32_bf16 v[62:65], v[166:169], v[214:217], v[62:65]
	v_mfma_f32_16x16x32_bf16 v[58:61], v[174:177], v[214:217], v[58:61]
	v_mfma_f32_16x16x32_bf16 v[50:53], v[166:169], v[222:225], v[50:53]
	v_mfma_f32_16x16x32_bf16 v[42:45], v[174:177], v[222:225], v[42:45]
	v_mfma_f32_16x16x32_bf16 v[34:37], v[166:169], v[230:233], v[34:37]
	v_mfma_f32_16x16x32_bf16 v[26:29], v[174:177], v[230:233], v[26:29]
	v_mfma_f32_16x16x32_bf16 v[18:21], v[166:169], v[238:241], v[18:21]
	v_mfma_f32_16x16x32_bf16 v[10:13], v[174:177], v[238:241], v[10:13]
	s_setprio 0
	s_setprio 1
	v_mfma_f32_16x16x32_bf16 v[54:57], v[178:181], v[210:213], v[54:57]
	v_mfma_f32_16x16x32_bf16 v[46:49], v[202:205], v[210:213], v[46:49]
	v_mfma_f32_16x16x32_bf16 v[38:41], v[178:181], v[218:221], v[38:41]
	v_mfma_f32_16x16x32_bf16 v[30:33], v[202:205], v[218:221], v[30:33]
	v_mfma_f32_16x16x32_bf16 v[22:25], v[178:181], v[226:229], v[22:25]
	v_mfma_f32_16x16x32_bf16 v[14:17], v[202:205], v[226:229], v[14:17]
	v_mfma_f32_16x16x32_bf16 v[6:9], v[178:181], v[234:237], v[6:9]
	v_mfma_f32_16x16x32_bf16 v[2:5], v[202:205], v[234:237], v[2:5]
	v_mfma_f32_16x16x32_bf16 v[54:57], v[198:201], v[214:217], v[54:57]
	v_mfma_f32_16x16x32_bf16 v[46:49], v[206:209], v[214:217], v[46:49]
	v_mfma_f32_16x16x32_bf16 v[38:41], v[198:201], v[222:225], v[38:41]
	v_mfma_f32_16x16x32_bf16 v[30:33], v[206:209], v[222:225], v[30:33]
	v_mfma_f32_16x16x32_bf16 v[22:25], v[198:201], v[230:233], v[22:25]
	v_mfma_f32_16x16x32_bf16 v[14:17], v[206:209], v[230:233], v[14:17]
	v_mfma_f32_16x16x32_bf16 v[6:9], v[198:201], v[238:241], v[6:9]
	v_mfma_f32_16x16x32_bf16 v[2:5], v[206:209], v[238:241], v[2:5]
	s_setprio 0
	s_barrier
; #define PG8_STAGE(bufoff, gbase, voff) do { _Pragma("unroll") for (int _i = 0; _i < 2; ++_i) \
;         __builtin_amdgcn_global_load_lds((const unsigned*)((const char*)(gbase) + (voff)[_i]), (LAS unsigned*)(lds + (bufoff) + ldsw + _i * 8192), 16, 0, 0); } while (0)
; #define PG8_LDA(dst, b, h) do { _Pragma("unroll") for (int m = 0; m < 4; ++m) _Pragma("unroll") for (int k = 0; k < 2; ++k) dst[m][k] = *(const LAS bf16x8*)(lds + PG8_SA(b, h) + aoff + m * 2048 + k * 1024); } while (0)
; #define PG8_LDB(dst, b, h) do { _Pragma("unroll") for (int n = 0; n < 2; ++n) _Pragma("unroll") for (int k = 0; k < 2; ++k) dst[n][k] = *(const LAS bf16x8*)(lds + PG8_SB(b, h) + boff + n * 2048 + k * 1024); } while (0)
; #define PG8_MMA(ai, bj, At, Bt) do { __builtin_amdgcn_s_setprio(1); _Pragma("unroll") for (int m = 0; m < 4; ++m) _Pragma("unroll") for (int n = 0; n < 2; ++n) _Pragma("unroll") for (int k = 0; k < 2; ++k) \
;         acc[ai][bj][m][n] = __builtin_amdgcn_mfma_f32_16x16x32_bf16(Bt[n][k], At[m][k], acc[ai][bj][m][n], 0, 0, 0); __builtin_amdgcn_s_setprio(0); } while (0)
; #define PG8_WAIT_V(n) asm volatile("s_waitcnt vmcnt(" #n ")" ::: "memory")
; #define PG8_WAIT_L(n) asm volatile("s_waitcnt lgkmcnt(" #n ")" ::: "memory")
; #define PG8_BAR __builtin_amdgcn_s_barrier()
; #define PG8_SCHED __builtin_amdgcn_sched_barrier(0)
; template <class Epi, class Sched>
; __device__ __forceinline__ void gemm_phase(LAS unsigned char* lds, const Gemm g, const Sched& S, const Epi& E, const int tid) {
;     ...
;             PG8_LDB(B0, 1, 0); PG8_LDB(B1, 1, 1); PG8_SCHED; PG8_LDA(At, 1, 0); PG8_STAGE(PG8_SA(0, 1), a2 + hstep, voffA);
;             PG8_WAIT_V(8); PG8_WAIT_L(0); PG8_BAR; PG8_MMA(0, 0, At, B0); PG8_MMA(0, 1, At, B1); PG8_BAR; PG8_SCHED;
	s_add_i32 s30, 0, 0x18000
	v_add_u32_e32 v161, s30, v156
	s_add_i32 s81, 0, 0x1c000
	ds_read_b128 v[162:165], v161
	ds_read_b128 v[166:169], v161 offset:1024
	ds_read_b128 v[170:173], v161 offset:2048
	ds_read_b128 v[174:177], v161 offset:3072
	v_add_u32_e32 v161, s81, v156
	ds_read_b128 v[178:181], v161
	ds_read_b128 v[198:201], v161 offset:1024
	ds_read_b128 v[202:205], v161 offset:2048
	ds_read_b128 v[206:209], v161 offset:3072
	s_add_u32 s26, s58, 0x40000
	s_addc_u32 s27, s59, 0
	s_mov_b32 m0, s53
	v_lshl_add_u64 v[244:245], s[26:27], 0, v[132:133]
	ds_read_b128 v[210:213], v160 offset:32768
	ds_read_b128 v[214:217], v160 offset:33792
	ds_read_b128 v[218:221], v160 offset:34816
	ds_read_b128 v[222:225], v160 offset:35840
	ds_read_b128 v[226:229], v160 offset:36864
	ds_read_b128 v[230:233], v160 offset:37888
	ds_read_b128 v[234:237], v160 offset:38912
	ds_read_b128 v[238:241], v160 offset:39936
	global_load_lds_dwordx4 v[244:245], off
	v_lshl_add_u64 v[244:245], s[26:27], 0, v[134:135]
	s_mov_b32 m0, s60
	s_nop 0
	global_load_lds_dwordx4 v[244:245], off
	s_waitcnt vmcnt(8)
	s_waitcnt lgkmcnt(0)
	s_barrier
	s_setprio 1
	s_waitcnt lgkmcnt(0)
	v_mfma_f32_16x16x32_bf16 v[126:129], v[162:165], v[210:213], v[126:129]
	v_mfma_f32_16x16x32_bf16 v[122:125], v[170:173], v[210:213], v[122:125]
	v_mfma_f32_16x16x32_bf16 v[114:117], v[162:165], v[218:221], v[114:117]
	v_mfma_f32_16x16x32_bf16 v[106:109], v[170:173], v[218:221], v[106:109]
	v_mfma_f32_16x16x32_bf16 v[98:101], v[162:165], v[226:229], v[98:101]
	v_mfma_f32_16x16x32_bf16 v[90:93], v[170:173], v[226:229], v[90:93]
	v_mfma_f32_16x16x32_bf16 v[82:85], v[162:165], v[234:237], v[82:85]
	v_mfma_f32_16x16x32_bf16 v[74:77], v[170:173], v[234:237], v[74:77]
	v_mfma_f32_16x16x32_bf16 v[126:129], v[166:169], v[214:217], v[126:129]
	v_mfma_f32_16x16x32_bf16 v[122:125], v[174:177], v[214:217], v[122:125]
	v_mfma_f32_16x16x32_bf16 v[114:117], v[166:169], v[222:225], v[114:117]
	v_mfma_f32_16x16x32_bf16 v[106:109], v[174:177], v[222:225], v[106:109]
	v_mfma_f32_16x16x32_bf16 v[98:101], v[166:169], v[230:233], v[98:101]
	v_mfma_f32_16x16x32_bf16 v[90:93], v[174:177], v[230:233], v[90:93]
	v_mfma_f32_16x16x32_bf16 v[82:85], v[166:169], v[238:241], v[82:85]
	v_mfma_f32_16x16x32_bf16 v[74:77], v[174:177], v[238:241], v[74:77]
	s_setprio 0
	s_setprio 1
	v_mfma_f32_16x16x32_bf16 v[118:121], v[178:181], v[210:213], v[118:121]
	v_mfma_f32_16x16x32_bf16 v[110:113], v[202:205], v[210:213], v[110:113]
	v_mfma_f32_16x16x32_bf16 v[102:105], v[178:181], v[218:221], v[102:105]
	v_mfma_f32_16x16x32_bf16 v[94:97], v[202:205], v[218:221], v[94:97]
	v_mfma_f32_16x16x32_bf16 v[86:89], v[178:181], v[226:229], v[86:89]
	v_mfma_f32_16x16x32_bf16 v[78:81], v[202:205], v[226:229], v[78:81]
	v_mfma_f32_16x16x32_bf16 v[70:73], v[178:181], v[234:237], v[70:73]
	v_mfma_f32_16x16x32_bf16 v[66:69], v[202:205], v[234:237], v[66:69]
	v_mfma_f32_16x16x32_bf16 v[118:121], v[198:201], v[214:217], v[118:121]
	v_mfma_f32_16x16x32_bf16 v[110:113], v[206:209], v[214:217], v[110:113]
	v_mfma_f32_16x16x32_bf16 v[102:105], v[198:201], v[222:225], v[102:105]
	v_mfma_f32_16x16x32_bf16 v[94:97], v[206:209], v[222:225], v[94:97]
	v_mfma_f32_16x16x32_bf16 v[86:89], v[198:201], v[230:233], v[86:89]
	v_mfma_f32_16x16x32_bf16 v[78:81], v[206:209], v[230:233], v[78:81]
	v_mfma_f32_16x16x32_bf16 v[70:73], v[198:201], v[238:241], v[70:73]
	v_mfma_f32_16x16x32_bf16 v[66:69], v[206:209], v[238:241], v[66:69]
	s_setprio 0
	s_barrier
; #define LAS __attribute__((address_space(3)))
; #define PG8_STAGE(bufoff, gbase, voff) do { _Pragma("unroll") for (int _i = 0; _i < 2; ++_i) \
;         __builtin_amdgcn_global_load_lds((const unsigned*)((const char*)(gbase) + (voff)[_i]), (LAS unsigned*)(lds + (bufoff) + ldsw + _i * 8192), 16, 0, 0); } while (0)
; #define PG8_LDA(dst, b, h) do { _Pragma("unroll") for (int m = 0; m < 4; ++m) _Pragma("unroll") for (int k = 0; k < 2; ++k) dst[m][k] = *(const LAS bf16x8*)(lds + PG8_SA(b, h) + aoff + m * 2048 + k * 1024); } while (0)
; #define PG8_MMA(ai, bj, At, Bt) do { __builtin_amdgcn_s_setprio(1); _Pragma("unroll") for (int m = 0; m < 4; ++m) _Pragma("unroll") for (int n = 0; n < 2; ++n) _Pragma("unroll") for (int k = 0; k < 2; ++k) \
;         acc[ai][bj][m][n] = __builtin_amdgcn_mfma_f32_16x16x32_bf16(Bt[n][k], At[m][k], acc[ai][bj][m][n], 0, 0, 0); __builtin_amdgcn_s_setprio(0); } while (0)
; #define PG8_WAIT_V(n) asm volatile("s_waitcnt vmcnt(" #n ")" ::: "memory")
; #define PG8_WAIT_L(n) asm volatile("s_waitcnt lgkmcnt(" #n ")" ::: "memory")
; #define PG8_BAR __builtin_amdgcn_s_barrier()
; #define PG8_SCHED __builtin_amdgcn_sched_barrier(0)
; __device__ __forceinline__ float row_scale(const float* ssq, int row) {
;     const f32x4* p = (const f32x4*)(ssq + (size_t)row * 16); const f32x4 a = p[0], b = p[1], c = p[2], d = p[3];
; template <class Epi, class Sched>
; __device__ __forceinline__ void gemm_phase(LAS unsigned char* lds, const Gemm g, const Sched& S, const Epi& E, const int tid) {
;     ...
;             PG8_LDA(At, 1, 1); PG8_STAGE(PG8_SB(1, 0), b3, voffB); PG8_STAGE(PG8_SB(1, 1), b3 + hstep, voffB); PG8_STAGE(PG8_SA(1, 0), a3, voffA);
;             PG8_WAIT_V(8); PG8_WAIT_L(0); PG8_BAR; PG8_MMA(1, 0, At, B0); PG8_MMA(1, 1, At, B1); PG8_BAR; PG8_SCHED;
;         }
;         if (wr == 0) PG8_BAR;
;     __device__ __forceinline__ void prep(const pg8::Unit& u, LAS unsigned char* sp, int tid) const {
;         if (tid < 256) ((LAS float*)sp)[tid] = row_scale(ssq, u.pm * 256 + tid);
	s_add_i32 s26, s30, s28
	v_lshl_add_u64 v[142:143], v[142:143], 0, s[34:35]
	s_mov_b32 m0, s26
	ds_read_b128 v[210:213], v160 offset:49152
	ds_read_b128 v[214:217], v160 offset:50176
	ds_read_b128 v[218:221], v160 offset:51200
	ds_read_b128 v[222:225], v160 offset:52224
	ds_read_b128 v[226:229], v160 offset:53248
	ds_read_b128 v[230:233], v160 offset:54272
	ds_read_b128 v[234:237], v160 offset:55296
	ds_read_b128 v[238:241], v160 offset:56320
	global_load_lds_dwordx4 v[142:143], off
	s_add_i32 m0, s26, 0x2000
	s_add_u32 s26, s56, 0x40080
	v_lshl_add_u64 v[142:143], v[182:183], 0, s[34:35]
	s_addc_u32 s27, s57, 0
	s_add_i32 s30, s81, s28
	global_load_lds_dwordx4 v[142:143], off
	v_lshl_add_u64 v[142:143], s[26:27], 0, v[0:1]
	s_mov_b32 m0, s30
	s_nop 0
	global_load_lds_dwordx4 v[142:143], off
	v_lshl_add_u64 v[142:143], s[26:27], 0, v[136:137]
	s_add_i32 m0, s30, 0x2000
	s_nop 0
	global_load_lds_dwordx4 v[142:143], off
	v_lshl_add_u64 v[142:143], v[192:193], 0, s[34:35]
	s_mov_b32 m0, s63
	s_nop 0
	global_load_lds_dwordx4 v[142:143], off
	v_lshl_add_u64 v[142:143], v[242:243], 0, s[34:35]
	s_mov_b32 m0, s64
	s_nop 0
	global_load_lds_dwordx4 v[142:143], off
	s_waitcnt vmcnt(8)
	s_waitcnt lgkmcnt(0)
	s_barrier
	s_setprio 1
	s_waitcnt lgkmcnt(0)
	v_mfma_f32_16x16x32_bf16 v[62:65], v[162:165], v[210:213], v[62:65]
	v_mfma_f32_16x16x32_bf16 v[58:61], v[170:173], v[210:213], v[58:61]
	v_mfma_f32_16x16x32_bf16 v[50:53], v[162:165], v[218:221], v[50:53]
	v_mfma_f32_16x16x32_bf16 v[42:45], v[170:173], v[218:221], v[42:45]
	v_mfma_f32_16x16x32_bf16 v[34:37], v[162:165], v[226:229], v[34:37]
	v_mfma_f32_16x16x32_bf16 v[26:29], v[170:173], v[226:229], v[26:29]
	v_mfma_f32_16x16x32_bf16 v[18:21], v[162:165], v[234:237], v[18:21]
	v_mfma_f32_16x16x32_bf16 v[10:13], v[170:173], v[234:237], v[10:13]
	v_mfma_f32_16x16x32_bf16 v[62:65], v[166:169], v[214:217], v[62:65]
	v_mfma_f32_16x16x32_bf16 v[58:61], v[174:177], v[214:217], v[58:61]
	v_mfma_f32_16x16x32_bf16 v[50:53], v[166:169], v[222:225], v[50:53]
	v_mfma_f32_16x16x32_bf16 v[42:45], v[174:177], v[222:225], v[42:45]
	v_mfma_f32_16x16x32_bf16 v[34:37], v[166:169], v[230:233], v[34:37]
	v_mfma_f32_16x16x32_bf16 v[26:29], v[174:177], v[230:233], v[26:29]
	v_mfma_f32_16x16x32_bf16 v[18:21], v[166:169], v[238:241], v[18:21]
	v_mfma_f32_16x16x32_bf16 v[10:13], v[174:177], v[238:241], v[10:13]
	s_setprio 0
	s_setprio 1
	v_mfma_f32_16x16x32_bf16 v[54:57], v[178:181], v[210:213], v[54:57]
	v_mfma_f32_16x16x32_bf16 v[46:49], v[202:205], v[210:213], v[46:49]
	v_mfma_f32_16x16x32_bf16 v[38:41], v[178:181], v[218:221], v[38:41]
	v_mfma_f32_16x16x32_bf16 v[30:33], v[202:205], v[218:221], v[30:33]
	v_mfma_f32_16x16x32_bf16 v[22:25], v[178:181], v[226:229], v[22:25]
	v_mfma_f32_16x16x32_bf16 v[14:17], v[202:205], v[226:229], v[14:17]
	v_mfma_f32_16x16x32_bf16 v[6:9], v[178:181], v[234:237], v[6:9]
	v_mfma_f32_16x16x32_bf16 v[2:5], v[202:205], v[234:237], v[2:5]
	v_mfma_f32_16x16x32_bf16 v[54:57], v[198:201], v[214:217], v[54:57]
	v_mfma_f32_16x16x32_bf16 v[46:49], v[206:209], v[214:217], v[46:49]
	v_mfma_f32_16x16x32_bf16 v[38:41], v[198:201], v[222:225], v[38:41]
	v_mfma_f32_16x16x32_bf16 v[30:33], v[206:209], v[222:225], v[30:33]
	v_mfma_f32_16x16x32_bf16 v[22:25], v[198:201], v[230:233], v[22:25]
	v_mfma_f32_16x16x32_bf16 v[14:17], v[206:209], v[230:233], v[14:17]
	v_mfma_f32_16x16x32_bf16 v[6:9], v[198:201], v[238:241], v[6:9]
	v_mfma_f32_16x16x32_bf16 v[2:5], v[206:209], v[238:241], v[2:5]
	s_setprio 0
	s_barrier
	s_add_i32 s72, s72, 2
	s_add_u32 s54, s54, 0x100
	s_addc_u32 s55, s55, 0
	s_add_u32 s76, s76, 0x100
	s_addc_u32 s79, s79, 0
	s_cmp_gt_u32 s72, 13
	s_cbranch_scc0 .LBB0_30
	s_and_b64 vcc, exec, s[14:15]
	s_cbranch_vccz .LBB0_33
	s_barrier
.LBB0_33:
	s_mov_b32 s95, -2
	s_and_b64 s[84:85], s[4:5], s[6:7]
	s_and_saveexec_b64 s[88:89], s[84:85]
	s_cbranch_execz .Lpre6_skip
	v_lshl_add_u32 v214, s22, 8, v144
	v_ashrrev_i32_e32 v215, 31, v214
	v_lshlrev_b64 v[214:215], 6, v[214:215]
	v_lshl_add_u64 v[214:215], v[130:131], 0, v[214:215]
	global_load_dwordx4 v[198:201], v[214:215], off offset:48
	global_load_dwordx4 v[202:205], v[214:215], off offset:32
	global_load_dwordx4 v[206:209], v[214:215], off offset:16
	global_load_dwordx4 v[210:213], v[214:215], off
